# grid barrier: all pollers watch the cross-XCD arrival counter itself (release = last arrival), separate release word no longer written in the loop barrier
# speedup vs baseline: 1.0186x; 1.0014x over previous
; __device__ __forceinline__ unsigned xb_ld(unsigned* p)              { return __hip_atomic_load(p, __ATOMIC_RELAXED, __HIP_MEMORY_SCOPE_AGENT); }
; __device__ __forceinline__ unsigned xb_add(unsigned* p, unsigned v) { return __hip_atomic_fetch_add(p, v, __ATOMIC_RELAXED, __HIP_MEMORY_SCOPE_AGENT); }
; #define XB_SPIN(cond, bar) do { unsigned _sp = 0; while (cond) { __builtin_amdgcn_s_sleep(1); \
;     if ((++_sp & 255u) == 0u) { if (xb_ld(&(bar)[XB_TMO])) break; if (_sp > XB_SPIN_CAP) { atomicAdd(&(bar)[XB_TMO], 1u); break; } } } } while (0)
; __device__ __forceinline__ void xcd_barrier(const XcdBarrier& b) {
;     ...
;         const unsigned old = xb_add(&bar[XB_XSUB(b.x)], 1u);
;         const unsigned gen = old / nloc;
;         if (old + 1u == (gen + 1u) * nloc) {
;             __builtin_amdgcn_fence(__ATOMIC_RELEASE, "agent");
;             asm volatile("s_waitcnt vmcnt(0)" ::: "memory");
;             const unsigned og = xb_add(&bar[XB_TOP], 1u);
;             const unsigned tg = og / nx;
;             if (og + 1u == (tg + 1u) * nx) xb_add(&bar[XB_TOPGEN], 1u);
;             else XB_SPIN(xb_ld(&bar[XB_TOPGEN]) == tg, bar);
;             __builtin_amdgcn_fence(__ATOMIC_ACQUIRE, "agent");
;             xb_add(&bar[XB_XGEN(b.x)], 1u);
;             asm volatile("s_waitcnt vmcnt(0)" ::: "memory");
;         } else {
;             XB_SPIN(xb_ld(&bar[XB_XGEN(b.x)]) == gen, bar);
;             __builtin_amdgcn_fence(__ATOMIC_ACQUIRE, "agent");
;             asm volatile("s_waitcnt vmcnt(0)" ::: "memory");
.LBB0_1828:
	global_atomic_add v3, v[192:193], v206, off sc0
	v_cvt_f32_u32_e32 v1, v2
	v_sub_u32_e32 v4, 0, v2
	v_rcp_iflag_f32_e32 v1, v1
	s_nop 0
	v_mul_f32_e32 v1, 0x4f7ffffe, v1
	v_cvt_u32_f32_e32 v1, v1
	v_mul_lo_u32 v4, v4, v1
	v_mul_hi_u32 v4, v1, v4
	v_add_u32_e32 v1, v1, v4
	s_waitcnt vmcnt(0)
	v_mul_hi_u32 v1, v3, v1
	v_mul_lo_u32 v4, v1, v2
	v_sub_u32_e32 v4, v3, v4
	v_add_u32_e32 v5, 1, v1
	v_cmp_ge_u32_e32 vcc, v4, v2
	v_add_u32_e32 v3, 1, v3
	s_nop 0
	v_cndmask_b32_e32 v1, v1, v5, vcc
	v_sub_u32_e32 v5, v4, v2
	v_cndmask_b32_e32 v4, v4, v5, vcc
	v_add_u32_e32 v5, 1, v1
	v_cmp_ge_u32_e32 vcc, v4, v2
	s_nop 1
	v_cndmask_b32_e32 v1, v1, v5, vcc
	v_mul_lo_u32 v4, v2, v1
	v_add_u32_e32 v2, v4, v2
	v_cmp_ne_u32_e32 vcc, v3, v2
	s_and_saveexec_b64 s[2:3], vcc
	s_xor_b64 s[2:3], exec, s[2:3]
	s_cbranch_execz .LBB0_1842
	s_waitcnt lgkmcnt(0)
	v_add_u32_e32 v5, 1, v1
	v_mul_lo_u32 v5, v5, v0
	v_readlane_b32 s4, v251, 27
	v_readlane_b32 s5, v251, 28
	s_nop 4
	global_load_dword v0, v197, s[4:5] sc1
	s_waitcnt vmcnt(0)
	v_cmp_gt_u32_e32 vcc, v5, v0
	s_and_saveexec_b64 s[18:19], vcc
	s_cbranch_execz .LBB0_1841
	s_mov_b32 s21, 1
	s_mov_b64 s[24:25], 0
	s_branch .LBB0_1832

; __device__ __forceinline__ unsigned xb_ld(unsigned* p)              { return __hip_atomic_load(p, __ATOMIC_RELAXED, __HIP_MEMORY_SCOPE_AGENT); }
; #define XB_SPIN(cond, bar) do { unsigned _sp = 0; while (cond) { __builtin_amdgcn_s_sleep(1); \
;     if ((++_sp & 255u) == 0u) { if (xb_ld(&(bar)[XB_TMO])) break; if (_sp > XB_SPIN_CAP) { atomicAdd(&(bar)[XB_TMO], 1u); break; } } } } while (0)
; __device__ __forceinline__ void xcd_barrier(const XcdBarrier& b) {
;     ...
;             XB_SPIN(xb_ld(&bar[XB_XGEN(b.x)]) == gen, bar);
.LBB0_1836:
	v_readlane_b32 s4, v251, 27
	v_readlane_b32 s5, v251, 28
	s_nop 4
	global_load_dword v0, v197, s[4:5] sc1
	s_add_i32 s21, s21, 1
	s_mov_b64 s[38:39], -1
	s_waitcnt vmcnt(0)
	v_cmp_le_u32_e32 vcc, v5, v0
	s_orn2_b64 s[34:35], vcc, exec
	s_branch .LBB0_1831

; __device__ __forceinline__ unsigned xb_ld(unsigned* p)              { return __hip_atomic_load(p, __ATOMIC_RELAXED, __HIP_MEMORY_SCOPE_AGENT); }
; __device__ __forceinline__ unsigned xb_add(unsigned* p, unsigned v) { return __hip_atomic_fetch_add(p, v, __ATOMIC_RELAXED, __HIP_MEMORY_SCOPE_AGENT); }
; #define XB_SPIN(cond, bar) do { unsigned _sp = 0; while (cond) { __builtin_amdgcn_s_sleep(1); \
;     if ((++_sp & 255u) == 0u) { if (xb_ld(&(bar)[XB_TMO])) break; if (_sp > XB_SPIN_CAP) { atomicAdd(&(bar)[XB_TMO], 1u); break; } } } } while (0)
; __device__ __forceinline__ void xcd_barrier(const XcdBarrier& b) {
;     ...
;             const unsigned og = xb_add(&bar[XB_TOP], 1u);
;             const unsigned tg = og / nx;
;             if (og + 1u == (tg + 1u) * nx) xb_add(&bar[XB_TOPGEN], 1u);
;             else XB_SPIN(xb_ld(&bar[XB_TOPGEN]) == tg, bar);
.LBB0_1845:
	s_or_b64 exec, exec, s[18:19]
	s_waitcnt vmcnt(0)
	v_readfirstlane_b32 s2, v2
	v_cvt_f32_u32_e32 v2, v0
	v_sub_u32_e32 v3, 0, v0
	v_add_u32_e32 v1, s2, v1
	v_readlane_b32 s2, v251, 29
	v_rcp_iflag_f32_e32 v2, v2
	v_readlane_b32 s3, v251, 30
	s_mov_b64 s[18:19], 0
	v_mul_f32_e32 v2, 0x4f7ffffe, v2
	v_cvt_u32_f32_e32 v2, v2
	v_mul_lo_u32 v3, v3, v2
	v_mul_hi_u32 v3, v2, v3
	v_add_u32_e32 v2, v2, v3
	v_mul_hi_u32 v2, v1, v2
	v_mul_lo_u32 v3, v2, v0
	v_sub_u32_e32 v3, v1, v3
	v_cmp_ge_u32_e32 vcc, v3, v0
	v_add_u32_e32 v4, 1, v2
	v_add_u32_e32 v1, 1, v1
	v_cndmask_b32_e32 v2, v2, v4, vcc
	v_sub_u32_e32 v4, v3, v0
	v_cndmask_b32_e32 v3, v3, v4, vcc
	v_cmp_ge_u32_e32 vcc, v3, v0
	v_add_u32_e32 v3, 1, v2
	s_nop 0
	v_cndmask_b32_e32 v2, v2, v3, vcc
	v_mul_lo_u32 v3, v0, v2
	v_add_u32_e32 v0, v3, v0
	v_mov_b32_e32 v5, v0
	v_cmp_ne_u32_e32 vcc, v1, v0
	v_mov_b64_e32 v[0:1], s[2:3]
	s_and_saveexec_b64 s[2:3], vcc
	s_cbranch_execz .LBB0_1857
	v_readlane_b32 s4, v251, 27
	v_readlane_b32 s5, v251, 28
	s_mov_b64 s[24:25], 0
	s_nop 3
	global_load_dword v0, v197, s[4:5] sc1
	s_waitcnt vmcnt(0)
	v_cmp_gt_u32_e32 vcc, v5, v0
	s_and_saveexec_b64 s[18:19], vcc
	s_cbranch_execz .LBB0_1856
	s_mov_b32 s21, 1
	s_branch .LBB0_1849

; __device__ __forceinline__ unsigned xb_ld(unsigned* p)              { return __hip_atomic_load(p, __ATOMIC_RELAXED, __HIP_MEMORY_SCOPE_AGENT); }
; #define XB_SPIN(cond, bar) do { unsigned _sp = 0; while (cond) { __builtin_amdgcn_s_sleep(1); \
;     if ((++_sp & 255u) == 0u) { if (xb_ld(&(bar)[XB_TMO])) break; if (_sp > XB_SPIN_CAP) { atomicAdd(&(bar)[XB_TMO], 1u); break; } } } } while (0)
; __device__ __forceinline__ void xcd_barrier(const XcdBarrier& b) {
;     ...
;             else XB_SPIN(xb_ld(&bar[XB_TOPGEN]) == tg, bar);
.LBB0_1853:
	v_readlane_b32 s4, v251, 27
	v_readlane_b32 s5, v251, 28
	s_add_i32 s21, s21, 1
	s_mov_b64 s[38:39], -1
	s_nop 2
	global_load_dword v0, v197, s[4:5] sc1
	s_waitcnt vmcnt(0)
	v_cmp_le_u32_e32 vcc, v5, v0
	s_orn2_b64 s[34:35], vcc, exec
	s_branch .LBB0_1848
